# ffup epilogue LDS writes lane-pair packed too (16 ds_write_b32 per tile instead of 32 ds_write_b16); ev_in/odin store section uses counted lgkmcnt waits (15/10/0) so the first stores issue while the l
# speedup vs baseline: 1.0030x; 1.0030x over previous
.Levin1_notr:
	s_cmp_eq_u32 s24, 2
	s_cbranch_scc1 .LBB0_259
	s_cmp_eq_u32 s24, 7
	s_cbranch_scc1 .LBB0_259
	s_cmp_ge_u32 s24, 3
	s_cselect_b32 s2, 1, 0
	s_sub_u32 s2, s24, s2
	s_cmp_ge_u32 s24, 8
	s_cselect_b32 s3, 1, 0
	s_sub_u32 s2, s2, s3
	s_lshl_b32 s2, s2, 9
	s_add_u32 s2, s2, s0
	s_lshl_b32 s2, s2, 1
	s_mul_i32 s3, s1, 0x1c00
	s_add_u32 s2, s2, s3
	s_add_u32 s98, s90, 0x3971900
	s_addc_u32 s99, s91, 0
	s_add_u32 s98, s98, s2
	s_addc_u32 s99, s99, 0
	v_and_b32_e32 v120, 1, v118
	v_lshlrev_b32_e32 v121, 6, v120
	v_sub_u32_e32 v121, v121, v120
	v_sub_u32_e32 v121, v121, v120
	v_add_u32_e32 v121, v121, v112
	v_cmp_eq_u32_e32 vcc, 1, v120
	v_mov_b32_e32 v120, 0x05040100
	v_mov_b32_e32 v122, 0x03020706
	s_nop 1
	v_cndmask_b32_e32 v120, v120, v122, vcc
	v_cvt_pk_bf16_f32 v64, v48, v49
	v_cvt_pk_bf16_f32 v65, v50, v51
	v_cvt_pk_bf16_f32 v66, v52, v53
	v_cvt_pk_bf16_f32 v67, v54, v55
	v_cvt_pk_bf16_f32 v68, v56, v57
	v_cvt_pk_bf16_f32 v69, v58, v59
	v_cvt_pk_bf16_f32 v70, v60, v61
	v_cvt_pk_bf16_f32 v71, v62, v63
	v_mov_b32_dpp v72, v64 quad_perm:[1,0,3,2] row_mask:0xf bank_mask:0xf
	v_mov_b32_dpp v73, v65 quad_perm:[1,0,3,2] row_mask:0xf bank_mask:0xf
	v_mov_b32_dpp v74, v66 quad_perm:[1,0,3,2] row_mask:0xf bank_mask:0xf
	v_mov_b32_dpp v75, v67 quad_perm:[1,0,3,2] row_mask:0xf bank_mask:0xf
	v_mov_b32_dpp v76, v68 quad_perm:[1,0,3,2] row_mask:0xf bank_mask:0xf
	v_mov_b32_dpp v77, v69 quad_perm:[1,0,3,2] row_mask:0xf bank_mask:0xf
	v_mov_b32_dpp v78, v70 quad_perm:[1,0,3,2] row_mask:0xf bank_mask:0xf
	v_mov_b32_dpp v79, v71 quad_perm:[1,0,3,2] row_mask:0xf bank_mask:0xf
	v_perm_b32 v72, v72, v64, v120
	v_perm_b32 v73, v73, v65, v120
	v_perm_b32 v74, v74, v66, v120
	v_perm_b32 v75, v75, v67, v120
	v_perm_b32 v76, v76, v68, v120
	v_perm_b32 v77, v77, v69, v120
	v_perm_b32 v78, v78, v70, v120
	v_perm_b32 v79, v79, v71, v120
	ds_write_b32 v121, v72
	ds_write_b32 v121, v73 offset:128
	ds_write_b32 v121, v74 offset:512
	ds_write_b32 v121, v75 offset:640
	ds_write_b32 v121, v76 offset:1024
	ds_write_b32 v121, v77 offset:1152
	ds_write_b32 v121, v78 offset:1536
	ds_write_b32 v121, v79 offset:1664
	ds_read_b128 v[80:83], v113
	ds_read_b128 v[84:87], v113 offset:1024
	v_cvt_pk_bf16_f32 v64, v16, v17
	v_cvt_pk_bf16_f32 v65, v18, v19
	v_cvt_pk_bf16_f32 v66, v20, v21
	v_cvt_pk_bf16_f32 v67, v22, v23
	v_cvt_pk_bf16_f32 v68, v24, v25
	v_cvt_pk_bf16_f32 v69, v26, v27
	v_cvt_pk_bf16_f32 v70, v28, v29
	v_cvt_pk_bf16_f32 v71, v30, v31
	v_mov_b32_dpp v72, v64 quad_perm:[1,0,3,2] row_mask:0xf bank_mask:0xf
	v_mov_b32_dpp v73, v65 quad_perm:[1,0,3,2] row_mask:0xf bank_mask:0xf
	v_mov_b32_dpp v74, v66 quad_perm:[1,0,3,2] row_mask:0xf bank_mask:0xf
	v_mov_b32_dpp v75, v67 quad_perm:[1,0,3,2] row_mask:0xf bank_mask:0xf
	v_mov_b32_dpp v76, v68 quad_perm:[1,0,3,2] row_mask:0xf bank_mask:0xf
	v_mov_b32_dpp v77, v69 quad_perm:[1,0,3,2] row_mask:0xf bank_mask:0xf
	v_mov_b32_dpp v78, v70 quad_perm:[1,0,3,2] row_mask:0xf bank_mask:0xf
	v_mov_b32_dpp v79, v71 quad_perm:[1,0,3,2] row_mask:0xf bank_mask:0xf
	v_perm_b32 v72, v72, v64, v120
	v_perm_b32 v73, v73, v65, v120
	v_perm_b32 v74, v74, v66, v120
	v_perm_b32 v75, v75, v67, v120
	v_perm_b32 v76, v76, v68, v120
	v_perm_b32 v77, v77, v69, v120
	v_perm_b32 v78, v78, v70, v120
	v_perm_b32 v79, v79, v71, v120
	ds_write_b32 v121, v72
	ds_write_b32 v121, v73 offset:128
	ds_write_b32 v121, v74 offset:512
	ds_write_b32 v121, v75 offset:640
	ds_write_b32 v121, v76 offset:1024
	ds_write_b32 v121, v77 offset:1152
	ds_write_b32 v121, v78 offset:1536
	ds_write_b32 v121, v79 offset:1664
	ds_read_b128 v[88:91], v113
	ds_read_b128 v[92:95], v113 offset:1024
	v_cvt_pk_bf16_f32 v64, v32, v33
	v_cvt_pk_bf16_f32 v65, v34, v35
	v_cvt_pk_bf16_f32 v66, v36, v37
	v_cvt_pk_bf16_f32 v67, v38, v39
	v_cvt_pk_bf16_f32 v68, v40, v41
	v_cvt_pk_bf16_f32 v69, v42, v43
	v_cvt_pk_bf16_f32 v70, v44, v45
	v_cvt_pk_bf16_f32 v71, v46, v47
	v_mov_b32_dpp v72, v64 quad_perm:[1,0,3,2] row_mask:0xf bank_mask:0xf
	v_mov_b32_dpp v73, v65 quad_perm:[1,0,3,2] row_mask:0xf bank_mask:0xf
	v_mov_b32_dpp v74, v66 quad_perm:[1,0,3,2] row_mask:0xf bank_mask:0xf
	v_mov_b32_dpp v75, v67 quad_perm:[1,0,3,2] row_mask:0xf bank_mask:0xf
	v_mov_b32_dpp v76, v68 quad_perm:[1,0,3,2] row_mask:0xf bank_mask:0xf
	v_mov_b32_dpp v77, v69 quad_perm:[1,0,3,2] row_mask:0xf bank_mask:0xf
	v_mov_b32_dpp v78, v70 quad_perm:[1,0,3,2] row_mask:0xf bank_mask:0xf
	v_mov_b32_dpp v79, v71 quad_perm:[1,0,3,2] row_mask:0xf bank_mask:0xf
	v_perm_b32 v72, v72, v64, v120
	v_perm_b32 v73, v73, v65, v120
	v_perm_b32 v74, v74, v66, v120
	v_perm_b32 v75, v75, v67, v120
	v_perm_b32 v76, v76, v68, v120
	v_perm_b32 v77, v77, v69, v120
	v_perm_b32 v78, v78, v70, v120
	v_perm_b32 v79, v79, v71, v120
	ds_write_b32 v121, v72
	ds_write_b32 v121, v73 offset:128
	ds_write_b32 v121, v74 offset:512
	ds_write_b32 v121, v75 offset:640
	ds_write_b32 v121, v76 offset:1024
	ds_write_b32 v121, v77 offset:1152
	ds_write_b32 v121, v78 offset:1536
	ds_write_b32 v121, v79 offset:1664
	ds_read_b128 v[96:99], v113
	ds_read_b128 v[100:103], v113 offset:1024
	v_cvt_pk_bf16_f32 v64, v0, v1
	v_cvt_pk_bf16_f32 v65, v2, v3
	v_cvt_pk_bf16_f32 v66, v4, v5
	v_cvt_pk_bf16_f32 v67, v6, v7
	v_cvt_pk_bf16_f32 v68, v8, v9
	v_cvt_pk_bf16_f32 v69, v10, v11
	v_cvt_pk_bf16_f32 v70, v12, v13
	v_cvt_pk_bf16_f32 v71, v14, v15
	v_mov_b32_dpp v72, v64 quad_perm:[1,0,3,2] row_mask:0xf bank_mask:0xf
	v_mov_b32_dpp v73, v65 quad_perm:[1,0,3,2] row_mask:0xf bank_mask:0xf
	v_mov_b32_dpp v74, v66 quad_perm:[1,0,3,2] row_mask:0xf bank_mask:0xf
	v_mov_b32_dpp v75, v67 quad_perm:[1,0,3,2] row_mask:0xf bank_mask:0xf
	v_mov_b32_dpp v76, v68 quad_perm:[1,0,3,2] row_mask:0xf bank_mask:0xf
	v_mov_b32_dpp v77, v69 quad_perm:[1,0,3,2] row_mask:0xf bank_mask:0xf
	v_mov_b32_dpp v78, v70 quad_perm:[1,0,3,2] row_mask:0xf bank_mask:0xf
	v_mov_b32_dpp v79, v71 quad_perm:[1,0,3,2] row_mask:0xf bank_mask:0xf
	v_perm_b32 v72, v72, v64, v120
	v_perm_b32 v73, v73, v65, v120
	v_perm_b32 v74, v74, v66, v120
	v_perm_b32 v75, v75, v67, v120
	v_perm_b32 v76, v76, v68, v120
	v_perm_b32 v77, v77, v69, v120
	v_perm_b32 v78, v78, v70, v120
	v_perm_b32 v79, v79, v71, v120
	ds_write_b32 v121, v72
	ds_write_b32 v121, v73 offset:128
	ds_write_b32 v121, v74 offset:512
	ds_write_b32 v121, v75 offset:640
	ds_write_b32 v121, v76 offset:1024
	ds_write_b32 v121, v77 offset:1152
	ds_write_b32 v121, v78 offset:1536
	ds_write_b32 v121, v79 offset:1664
	ds_read_b128 v[104:107], v113
	ds_read_b128 v[108:111], v113 offset:1024
	s_waitcnt lgkmcnt(15)
	global_store_dwordx4 v114, v[80:83], s[98:99]
	s_add_u32 s100, s98, 0x1c000
	s_addc_u32 s101, s99, 0
	global_store_dwordx4 v114, v[84:87], s[100:101]
	global_store_dwordx4 v114, v[88:91], s[98:99] offset:64
	global_store_dwordx4 v114, v[92:95], s[100:101] offset:64
	s_add_u32 s98, s98, 0x38000
	s_addc_u32 s99, s99, 0
	s_waitcnt lgkmcnt(10)
	global_store_dwordx4 v114, v[96:99], s[98:99]
	s_add_u32 s100, s98, 0x1c000
	s_addc_u32 s101, s99, 0
	global_store_dwordx4 v114, v[100:103], s[100:101]
	s_waitcnt lgkmcnt(0)
	global_store_dwordx4 v114, v[104:107], s[98:99] offset:64
	global_store_dwordx4 v114, v[108:111], s[100:101] offset:64
	s_branch .LBB0_259

.LBB0_1034:
	v_lshl_or_b32 v115, v183, 3, v191
	v_lshrrev_b32_e32 v116, 6, v115
	v_and_b32_e32 v117, 63, v115
	v_lshlrev_b32_e32 v113, 11, v116
	v_add_u32_e32 v113, 0x10000, v113
	v_readfirstlane_b32 s100, v116
	v_and_b32_e32 v112, 31, v117
	v_lshl_add_u32 v112, v112, 1, v113
	v_lshrrev_b32_e32 v116, 5, v117
	v_lshl_add_u32 v112, v116, 8, v112
	v_lshl_add_u32 v113, v117, 4, v113
	v_lshrrev_b32_e32 v116, 2, v117
	v_mul_u32_u24_e32 v116, 0x1600, v116
	v_and_b32_e32 v114, 3, v117
	v_lshl_add_u32 v114, v114, 4, v116
	v_and_b32_e32 v118, 1, v117
	v_lshlrev_b32_e32 v119, 6, v118
	v_sub_u32_e32 v119, v119, v118
	v_sub_u32_e32 v119, v119, v118
	v_add_u32_e32 v119, v119, v112
	v_cmp_eq_u32_e32 vcc, 1, v118
	v_mov_b32_e32 v118, 0x05040100
	v_mov_b32_e32 v115, 0x03020706
	s_nop 1
	v_cndmask_b32_e32 v118, v118, v115, vcc
	s_lshr_b32 s101, s100, 1
	s_lshl_b32 s101, s101, 6
	s_add_u32 s101, s101, s48
	s_mul_i32 s101, s101, 0x1600
	s_and_b32 s100, s100, 1
	s_lshl_b32 s100, s100, 6
	s_add_u32 s100, s100, s49
	s_add_u32 s101, s101, s100
	s_add_u32 s98, s90, 0x3971900
	s_addc_u32 s99, s91, 0
	s_add_u32 s98, s98, s101
	s_addc_u32 s99, s99, 0
	v_mul_f32_e32 v64, 0xbfb8aa3b, v48
	v_mul_f32_e32 v70, 0xbfb8aa3b, v49
	v_mul_f32_e32 v76, 0xbfb8aa3b, v50
	v_mul_f32_e32 v82, 0xbfb8aa3b, v51
	v_exp_f32_e32 v64, v64
	v_exp_f32_e32 v70, v70
	v_exp_f32_e32 v76, v76
	v_exp_f32_e32 v82, v82
	v_add_f32_e32 v64, 1.0, v64
	v_add_f32_e32 v70, 1.0, v70
	v_add_f32_e32 v76, 1.0, v76
	v_add_f32_e32 v82, 1.0, v82
	v_rcp_f32_e32 v66, v64
	v_rcp_f32_e32 v72, v70
	v_rcp_f32_e32 v78, v76
	v_rcp_f32_e32 v84, v82
	v_fma_f32 v69, -v64, v66, 1.0
	v_fma_f32 v75, -v70, v72, 1.0
	v_fma_f32 v81, -v76, v78, 1.0
	v_fma_f32 v87, -v82, v84, 1.0
	v_fmac_f32_e32 v66, v69, v66
	v_fmac_f32_e32 v72, v75, v72
	v_fmac_f32_e32 v78, v81, v78
	v_fmac_f32_e32 v84, v87, v84
	v_fma_f32 v69, -v64, v66, 1.0
	v_mul_f32_e32 v88, 0xbfb8aa3b, v52
	v_fma_f32 v75, -v70, v72, 1.0
	v_mul_f32_e32 v94, 0xbfb8aa3b, v53
	v_fma_f32 v81, -v76, v78, 1.0
	v_mul_f32_e32 v100, 0xbfb8aa3b, v54
	v_fma_f32 v87, -v82, v84, 1.0
	v_mul_f32_e32 v106, 0xbfb8aa3b, v55
	v_fma_f32 v68, v69, v66, v66
	v_exp_f32_e32 v88, v88
	v_fma_f32 v74, v75, v72, v72
	v_exp_f32_e32 v94, v94
	v_fma_f32 v80, v81, v78, v78
	v_exp_f32_e32 v100, v100
	v_fma_f32 v86, v87, v84, v84
	v_exp_f32_e32 v106, v106
	v_fma_f32 v69, -v64, v68, 1.0
	v_add_f32_e32 v88, 1.0, v88
	v_fma_f32 v75, -v70, v74, 1.0
	v_add_f32_e32 v94, 1.0, v94
	v_fma_f32 v81, -v76, v80, 1.0
	v_add_f32_e32 v100, 1.0, v100
	v_fma_f32 v87, -v82, v86, 1.0
	v_add_f32_e32 v106, 1.0, v106
	v_fma_f32 v65, v69, v66, v68
	v_rcp_f32_e32 v90, v88
	v_fma_f32 v71, v75, v72, v74
	v_rcp_f32_e32 v96, v94
	v_fma_f32 v77, v81, v78, v80
	v_rcp_f32_e32 v102, v100
	v_fma_f32 v83, v87, v84, v86
	v_rcp_f32_e32 v108, v106
	v_fma_f32 v93, -v88, v90, 1.0
	v_fma_f32 v99, -v94, v96, 1.0
	v_fma_f32 v105, -v100, v102, 1.0
	v_fma_f32 v111, -v106, v108, 1.0
	v_fmac_f32_e32 v90, v93, v90
	v_fmac_f32_e32 v96, v99, v96
	v_fmac_f32_e32 v102, v105, v102
	v_fmac_f32_e32 v108, v111, v108
	v_div_fixup_f32 v65, v65, v64, 1.0
	v_div_fixup_f32 v71, v71, v70, 1.0
	v_div_fixup_f32 v77, v77, v76, 1.0
	v_div_fixup_f32 v83, v83, v82, 1.0
	v_mul_f32_e32 v65, v48, v65
	v_mul_f32_e32 v71, v49, v71
	v_mul_f32_e32 v77, v50, v77
	v_mul_f32_e32 v83, v51, v83
	v_mul_f32_e32 v65, v32, v65
	v_mul_f32_e32 v71, v33, v71
	v_mul_f32_e32 v77, v34, v77
	v_mul_f32_e32 v83, v35, v83
	v_cvt_pk_bf16_f32 v65, v65, v71
	v_cvt_pk_bf16_f32 v77, v77, v83
	s_nop 1
	v_mov_b32_dpp v71, v65 quad_perm:[1,0,3,2] row_mask:0xf bank_mask:0xf
	v_mov_b32_dpp v83, v77 quad_perm:[1,0,3,2] row_mask:0xf bank_mask:0xf
	v_perm_b32 v71, v71, v65, v118
	v_perm_b32 v83, v83, v77, v118
	ds_write_b32 v119, v71
	ds_write_b32 v119, v83 offset:128
	v_fma_f32 v93, -v88, v90, 1.0
	v_mul_f32_e32 v64, 0xbfb8aa3b, v56
	v_fma_f32 v99, -v94, v96, 1.0
	v_mul_f32_e32 v70, 0xbfb8aa3b, v57
	v_fma_f32 v105, -v100, v102, 1.0
	v_mul_f32_e32 v76, 0xbfb8aa3b, v58
	v_fma_f32 v111, -v106, v108, 1.0
	v_mul_f32_e32 v82, 0xbfb8aa3b, v59
	v_fma_f32 v92, v93, v90, v90
	v_exp_f32_e32 v64, v64
	v_fma_f32 v98, v99, v96, v96
	v_exp_f32_e32 v70, v70
	v_fma_f32 v104, v105, v102, v102
	v_exp_f32_e32 v76, v76
	v_fma_f32 v110, v111, v108, v108
	v_exp_f32_e32 v82, v82
	v_fma_f32 v93, -v88, v92, 1.0
	v_add_f32_e32 v64, 1.0, v64
	v_fma_f32 v99, -v94, v98, 1.0
	v_add_f32_e32 v70, 1.0, v70
	v_fma_f32 v105, -v100, v104, 1.0
	v_add_f32_e32 v76, 1.0, v76
	v_fma_f32 v111, -v106, v110, 1.0
	v_add_f32_e32 v82, 1.0, v82
	v_fma_f32 v89, v93, v90, v92
	v_rcp_f32_e32 v66, v64
	v_fma_f32 v95, v99, v96, v98
	v_rcp_f32_e32 v72, v70
	v_fma_f32 v101, v105, v102, v104
	v_rcp_f32_e32 v78, v76
	v_fma_f32 v107, v111, v108, v110
	v_rcp_f32_e32 v84, v82
	v_fma_f32 v69, -v64, v66, 1.0
	v_fma_f32 v75, -v70, v72, 1.0
	v_fma_f32 v81, -v76, v78, 1.0
	v_fma_f32 v87, -v82, v84, 1.0
	v_fmac_f32_e32 v66, v69, v66
	v_fmac_f32_e32 v72, v75, v72
	v_fmac_f32_e32 v78, v81, v78
	v_fmac_f32_e32 v84, v87, v84
	v_div_fixup_f32 v89, v89, v88, 1.0
	v_div_fixup_f32 v95, v95, v94, 1.0
	v_div_fixup_f32 v101, v101, v100, 1.0
	v_div_fixup_f32 v107, v107, v106, 1.0
	v_mul_f32_e32 v89, v52, v89
	v_mul_f32_e32 v95, v53, v95
	v_mul_f32_e32 v101, v54, v101
	v_mul_f32_e32 v107, v55, v107
	v_mul_f32_e32 v89, v36, v89
	v_mul_f32_e32 v95, v37, v95
	v_mul_f32_e32 v101, v38, v101
	v_mul_f32_e32 v107, v39, v107
	v_cvt_pk_bf16_f32 v89, v89, v95
	v_cvt_pk_bf16_f32 v101, v101, v107
	s_nop 1
	v_mov_b32_dpp v95, v89 quad_perm:[1,0,3,2] row_mask:0xf bank_mask:0xf
	v_mov_b32_dpp v107, v101 quad_perm:[1,0,3,2] row_mask:0xf bank_mask:0xf
	v_perm_b32 v95, v95, v89, v118
	v_perm_b32 v107, v107, v101, v118
	ds_write_b32 v119, v95 offset:512
	ds_write_b32 v119, v107 offset:640
	v_fma_f32 v69, -v64, v66, 1.0
	v_mul_f32_e32 v88, 0xbfb8aa3b, v60
	v_fma_f32 v75, -v70, v72, 1.0
	v_mul_f32_e32 v94, 0xbfb8aa3b, v61
	v_fma_f32 v81, -v76, v78, 1.0
	v_mul_f32_e32 v100, 0xbfb8aa3b, v62
	v_fma_f32 v87, -v82, v84, 1.0
	v_mul_f32_e32 v106, 0xbfb8aa3b, v63
	v_fma_f32 v68, v69, v66, v66
	v_exp_f32_e32 v88, v88
	v_fma_f32 v74, v75, v72, v72
	v_exp_f32_e32 v94, v94
	v_fma_f32 v80, v81, v78, v78
	v_exp_f32_e32 v100, v100
	v_fma_f32 v86, v87, v84, v84
	v_exp_f32_e32 v106, v106
	v_fma_f32 v69, -v64, v68, 1.0
	v_add_f32_e32 v88, 1.0, v88
	v_fma_f32 v75, -v70, v74, 1.0
	v_add_f32_e32 v94, 1.0, v94
	v_fma_f32 v81, -v76, v80, 1.0
	v_add_f32_e32 v100, 1.0, v100
	v_fma_f32 v87, -v82, v86, 1.0
	v_add_f32_e32 v106, 1.0, v106
	v_fma_f32 v65, v69, v66, v68
	v_rcp_f32_e32 v90, v88
	v_fma_f32 v71, v75, v72, v74
	v_rcp_f32_e32 v96, v94
	v_fma_f32 v77, v81, v78, v80
	v_rcp_f32_e32 v102, v100
	v_fma_f32 v83, v87, v84, v86
	v_rcp_f32_e32 v108, v106
	v_fma_f32 v93, -v88, v90, 1.0
	v_fma_f32 v99, -v94, v96, 1.0
	v_fma_f32 v105, -v100, v102, 1.0
	v_fma_f32 v111, -v106, v108, 1.0
	v_fmac_f32_e32 v90, v93, v90
	v_fmac_f32_e32 v96, v99, v96
	v_fmac_f32_e32 v102, v105, v102
	v_fmac_f32_e32 v108, v111, v108
	v_div_fixup_f32 v65, v65, v64, 1.0
	v_div_fixup_f32 v71, v71, v70, 1.0
	v_div_fixup_f32 v77, v77, v76, 1.0
	v_div_fixup_f32 v83, v83, v82, 1.0
	v_mul_f32_e32 v65, v56, v65
	v_mul_f32_e32 v71, v57, v71
	v_mul_f32_e32 v77, v58, v77
	v_mul_f32_e32 v83, v59, v83
	v_mul_f32_e32 v65, v40, v65
	v_mul_f32_e32 v71, v41, v71
	v_mul_f32_e32 v77, v42, v77
	v_mul_f32_e32 v83, v43, v83
	v_cvt_pk_bf16_f32 v65, v65, v71
	v_cvt_pk_bf16_f32 v77, v77, v83
	s_nop 1
	v_mov_b32_dpp v71, v65 quad_perm:[1,0,3,2] row_mask:0xf bank_mask:0xf
	v_mov_b32_dpp v83, v77 quad_perm:[1,0,3,2] row_mask:0xf bank_mask:0xf
	v_perm_b32 v71, v71, v65, v118
	v_perm_b32 v83, v83, v77, v118
	ds_write_b32 v119, v71 offset:1024
	ds_write_b32 v119, v83 offset:1152
	v_fma_f32 v93, -v88, v90, 1.0
	v_mul_f32_e32 v64, 0xbfb8aa3b, v16
	v_fma_f32 v99, -v94, v96, 1.0
	v_mul_f32_e32 v70, 0xbfb8aa3b, v17
	v_fma_f32 v105, -v100, v102, 1.0
	v_mul_f32_e32 v76, 0xbfb8aa3b, v18
	v_fma_f32 v111, -v106, v108, 1.0
	v_mul_f32_e32 v82, 0xbfb8aa3b, v19
	v_fma_f32 v92, v93, v90, v90
	v_exp_f32_e32 v64, v64
	v_fma_f32 v98, v99, v96, v96
	v_exp_f32_e32 v70, v70
	v_fma_f32 v104, v105, v102, v102
	v_exp_f32_e32 v76, v76
	v_fma_f32 v110, v111, v108, v108
	v_exp_f32_e32 v82, v82
	v_fma_f32 v93, -v88, v92, 1.0
	v_add_f32_e32 v64, 1.0, v64
	v_fma_f32 v99, -v94, v98, 1.0
	v_add_f32_e32 v70, 1.0, v70
	v_fma_f32 v105, -v100, v104, 1.0
	v_add_f32_e32 v76, 1.0, v76
	v_fma_f32 v111, -v106, v110, 1.0
	v_add_f32_e32 v82, 1.0, v82
	v_fma_f32 v89, v93, v90, v92
	v_rcp_f32_e32 v66, v64
	v_fma_f32 v95, v99, v96, v98
	v_rcp_f32_e32 v72, v70
	v_fma_f32 v101, v105, v102, v104
	v_rcp_f32_e32 v78, v76
	v_fma_f32 v107, v111, v108, v110
	v_rcp_f32_e32 v84, v82
	v_fma_f32 v69, -v64, v66, 1.0
	v_fma_f32 v75, -v70, v72, 1.0
	v_fma_f32 v81, -v76, v78, 1.0
	v_fma_f32 v87, -v82, v84, 1.0
	v_fmac_f32_e32 v66, v69, v66
	v_fmac_f32_e32 v72, v75, v72
	v_fmac_f32_e32 v78, v81, v78
	v_fmac_f32_e32 v84, v87, v84
	v_div_fixup_f32 v89, v89, v88, 1.0
	v_div_fixup_f32 v95, v95, v94, 1.0
	v_div_fixup_f32 v101, v101, v100, 1.0
	v_div_fixup_f32 v107, v107, v106, 1.0
	v_mul_f32_e32 v89, v60, v89
	v_mul_f32_e32 v95, v61, v95
	v_mul_f32_e32 v101, v62, v101
	v_mul_f32_e32 v107, v63, v107
	v_mul_f32_e32 v89, v44, v89
	v_mul_f32_e32 v95, v45, v95
	v_mul_f32_e32 v101, v46, v101
	v_mul_f32_e32 v107, v47, v107
	v_cvt_pk_bf16_f32 v89, v89, v95
	v_cvt_pk_bf16_f32 v101, v101, v107
	s_nop 1
	v_mov_b32_dpp v95, v89 quad_perm:[1,0,3,2] row_mask:0xf bank_mask:0xf
	v_mov_b32_dpp v107, v101 quad_perm:[1,0,3,2] row_mask:0xf bank_mask:0xf
	v_perm_b32 v95, v95, v89, v118
	v_perm_b32 v107, v107, v101, v118
	ds_write_b32 v119, v95 offset:1536
	ds_write_b32 v119, v107 offset:1664
	ds_read_b128 v[120:123], v113
	ds_read_b128 v[124:127], v113 offset:1024
	v_fma_f32 v69, -v64, v66, 1.0
	v_mul_f32_e32 v88, 0xbfb8aa3b, v20
	v_fma_f32 v75, -v70, v72, 1.0
	v_mul_f32_e32 v94, 0xbfb8aa3b, v21
	v_fma_f32 v81, -v76, v78, 1.0
	v_mul_f32_e32 v100, 0xbfb8aa3b, v22
	v_fma_f32 v87, -v82, v84, 1.0
	v_mul_f32_e32 v106, 0xbfb8aa3b, v23
	v_fma_f32 v68, v69, v66, v66
	v_exp_f32_e32 v88, v88
	v_fma_f32 v74, v75, v72, v72
	v_exp_f32_e32 v94, v94
	v_fma_f32 v80, v81, v78, v78
	v_exp_f32_e32 v100, v100
	v_fma_f32 v86, v87, v84, v84
	v_exp_f32_e32 v106, v106
	v_fma_f32 v69, -v64, v68, 1.0
	v_add_f32_e32 v88, 1.0, v88
	v_fma_f32 v75, -v70, v74, 1.0
	v_add_f32_e32 v94, 1.0, v94
	v_fma_f32 v81, -v76, v80, 1.0
	v_add_f32_e32 v100, 1.0, v100
	v_fma_f32 v87, -v82, v86, 1.0
	v_add_f32_e32 v106, 1.0, v106
	v_fma_f32 v65, v69, v66, v68
	v_rcp_f32_e32 v90, v88
	v_fma_f32 v71, v75, v72, v74
	v_rcp_f32_e32 v96, v94
	v_fma_f32 v77, v81, v78, v80
	v_rcp_f32_e32 v102, v100
	v_fma_f32 v83, v87, v84, v86
	v_rcp_f32_e32 v108, v106
	v_fma_f32 v93, -v88, v90, 1.0
	v_fma_f32 v99, -v94, v96, 1.0
	v_fma_f32 v105, -v100, v102, 1.0
	v_fma_f32 v111, -v106, v108, 1.0
	v_fmac_f32_e32 v90, v93, v90
	v_fmac_f32_e32 v96, v99, v96
	v_fmac_f32_e32 v102, v105, v102
	v_fmac_f32_e32 v108, v111, v108
	v_div_fixup_f32 v65, v65, v64, 1.0
	v_div_fixup_f32 v71, v71, v70, 1.0
	v_div_fixup_f32 v77, v77, v76, 1.0
	v_div_fixup_f32 v83, v83, v82, 1.0
	v_mul_f32_e32 v65, v16, v65
	v_mul_f32_e32 v71, v17, v71
	v_mul_f32_e32 v77, v18, v77
	v_mul_f32_e32 v83, v19, v83
	v_mul_f32_e32 v65, v0, v65
	v_mul_f32_e32 v71, v1, v71
	v_mul_f32_e32 v77, v2, v77
	v_mul_f32_e32 v83, v3, v83
	v_cvt_pk_bf16_f32 v65, v65, v71
	v_cvt_pk_bf16_f32 v77, v77, v83
	s_nop 1
	v_mov_b32_dpp v71, v65 quad_perm:[1,0,3,2] row_mask:0xf bank_mask:0xf
	v_mov_b32_dpp v83, v77 quad_perm:[1,0,3,2] row_mask:0xf bank_mask:0xf
	v_perm_b32 v71, v71, v65, v118
	v_perm_b32 v83, v83, v77, v118
	ds_write_b32 v119, v71
	ds_write_b32 v119, v83 offset:128
	v_fma_f32 v93, -v88, v90, 1.0
	v_mul_f32_e32 v64, 0xbfb8aa3b, v24
	v_fma_f32 v99, -v94, v96, 1.0
	v_mul_f32_e32 v70, 0xbfb8aa3b, v25
	v_fma_f32 v105, -v100, v102, 1.0
	v_mul_f32_e32 v76, 0xbfb8aa3b, v26
	v_fma_f32 v111, -v106, v108, 1.0
	v_mul_f32_e32 v82, 0xbfb8aa3b, v27
	v_fma_f32 v92, v93, v90, v90
	v_exp_f32_e32 v64, v64
	v_fma_f32 v98, v99, v96, v96
	v_exp_f32_e32 v70, v70
	v_fma_f32 v104, v105, v102, v102
	v_exp_f32_e32 v76, v76
	v_fma_f32 v110, v111, v108, v108
	v_exp_f32_e32 v82, v82
	v_fma_f32 v93, -v88, v92, 1.0
	v_add_f32_e32 v64, 1.0, v64
	v_fma_f32 v99, -v94, v98, 1.0
	v_add_f32_e32 v70, 1.0, v70
	v_fma_f32 v105, -v100, v104, 1.0
	v_add_f32_e32 v76, 1.0, v76
	v_fma_f32 v111, -v106, v110, 1.0
	v_add_f32_e32 v82, 1.0, v82
	v_fma_f32 v89, v93, v90, v92
	v_rcp_f32_e32 v66, v64
	v_fma_f32 v95, v99, v96, v98
	v_rcp_f32_e32 v72, v70
	v_fma_f32 v101, v105, v102, v104
	v_rcp_f32_e32 v78, v76
	v_fma_f32 v107, v111, v108, v110
	v_rcp_f32_e32 v84, v82
	v_fma_f32 v69, -v64, v66, 1.0
	v_fma_f32 v75, -v70, v72, 1.0
	v_fma_f32 v81, -v76, v78, 1.0
	v_fma_f32 v87, -v82, v84, 1.0
	v_fmac_f32_e32 v66, v69, v66
	v_fmac_f32_e32 v72, v75, v72
	v_fmac_f32_e32 v78, v81, v78
	v_fmac_f32_e32 v84, v87, v84
	s_waitcnt lgkmcnt(0)
	global_store_dwordx4 v114, v[120:123], s[98:99]
	s_add_u32 s98, s98, 0x16000
	s_addc_u32 s99, s99, 0
	global_store_dwordx4 v114, v[124:127], s[98:99]
	s_add_u32 s98, s98, 0x16000
	s_addc_u32 s99, s99, 0
	v_div_fixup_f32 v89, v89, v88, 1.0
	v_div_fixup_f32 v95, v95, v94, 1.0
	v_div_fixup_f32 v101, v101, v100, 1.0
	v_div_fixup_f32 v107, v107, v106, 1.0
	v_mul_f32_e32 v89, v20, v89
	v_mul_f32_e32 v95, v21, v95
	v_mul_f32_e32 v101, v22, v101
	v_mul_f32_e32 v107, v23, v107
	v_mul_f32_e32 v89, v4, v89
	v_mul_f32_e32 v95, v5, v95
	v_mul_f32_e32 v101, v6, v101
	v_mul_f32_e32 v107, v7, v107
	v_cvt_pk_bf16_f32 v89, v89, v95
	v_cvt_pk_bf16_f32 v101, v101, v107
	s_nop 1
	v_mov_b32_dpp v95, v89 quad_perm:[1,0,3,2] row_mask:0xf bank_mask:0xf
	v_mov_b32_dpp v107, v101 quad_perm:[1,0,3,2] row_mask:0xf bank_mask:0xf
	v_perm_b32 v95, v95, v89, v118
	v_perm_b32 v107, v107, v101, v118
	ds_write_b32 v119, v95 offset:512
	ds_write_b32 v119, v107 offset:640
	v_fma_f32 v69, -v64, v66, 1.0
	v_mul_f32_e32 v88, 0xbfb8aa3b, v28
	v_fma_f32 v75, -v70, v72, 1.0
	v_mul_f32_e32 v94, 0xbfb8aa3b, v29
	v_fma_f32 v81, -v76, v78, 1.0
	v_mul_f32_e32 v100, 0xbfb8aa3b, v30
	v_fma_f32 v87, -v82, v84, 1.0
	v_mul_f32_e32 v106, 0xbfb8aa3b, v31
	v_fma_f32 v68, v69, v66, v66
	v_exp_f32_e32 v88, v88
	v_fma_f32 v74, v75, v72, v72
	v_exp_f32_e32 v94, v94
	v_fma_f32 v80, v81, v78, v78
	v_exp_f32_e32 v100, v100
	v_fma_f32 v86, v87, v84, v84
	v_exp_f32_e32 v106, v106
	v_fma_f32 v69, -v64, v68, 1.0
	v_add_f32_e32 v88, 1.0, v88
	v_fma_f32 v75, -v70, v74, 1.0
	v_add_f32_e32 v94, 1.0, v94
	v_fma_f32 v81, -v76, v80, 1.0
	v_add_f32_e32 v100, 1.0, v100
	v_fma_f32 v87, -v82, v86, 1.0
	v_add_f32_e32 v106, 1.0, v106
	v_fma_f32 v65, v69, v66, v68
	v_rcp_f32_e32 v90, v88
	v_fma_f32 v71, v75, v72, v74
	v_rcp_f32_e32 v96, v94
	v_fma_f32 v77, v81, v78, v80
	v_rcp_f32_e32 v102, v100
	v_fma_f32 v83, v87, v84, v86
	v_rcp_f32_e32 v108, v106
	v_fma_f32 v93, -v88, v90, 1.0
	v_fma_f32 v99, -v94, v96, 1.0
	v_fma_f32 v105, -v100, v102, 1.0
	v_fma_f32 v111, -v106, v108, 1.0
	v_fmac_f32_e32 v90, v93, v90
	v_fmac_f32_e32 v96, v99, v96
	v_fmac_f32_e32 v102, v105, v102
	v_fmac_f32_e32 v108, v111, v108
	v_div_fixup_f32 v65, v65, v64, 1.0
	v_div_fixup_f32 v71, v71, v70, 1.0
	v_div_fixup_f32 v77, v77, v76, 1.0
	v_div_fixup_f32 v83, v83, v82, 1.0
	v_mul_f32_e32 v65, v24, v65
	v_mul_f32_e32 v71, v25, v71
	v_mul_f32_e32 v77, v26, v77
	v_mul_f32_e32 v83, v27, v83
	v_mul_f32_e32 v65, v8, v65
	v_mul_f32_e32 v71, v9, v71
	v_mul_f32_e32 v77, v10, v77
	v_mul_f32_e32 v83, v11, v83
	v_cvt_pk_bf16_f32 v65, v65, v71
	v_cvt_pk_bf16_f32 v77, v77, v83
	s_nop 1
	v_mov_b32_dpp v71, v65 quad_perm:[1,0,3,2] row_mask:0xf bank_mask:0xf
	v_mov_b32_dpp v83, v77 quad_perm:[1,0,3,2] row_mask:0xf bank_mask:0xf
	v_perm_b32 v71, v71, v65, v118
	v_perm_b32 v83, v83, v77, v118
	ds_write_b32 v119, v71 offset:1024
	ds_write_b32 v119, v83 offset:1152
	v_fma_f32 v93, -v88, v90, 1.0
	v_fma_f32 v99, -v94, v96, 1.0
	v_fma_f32 v105, -v100, v102, 1.0
	v_fma_f32 v111, -v106, v108, 1.0
	v_fma_f32 v92, v93, v90, v90
	v_fma_f32 v98, v99, v96, v96
	v_fma_f32 v104, v105, v102, v102
	v_fma_f32 v110, v111, v108, v108
	v_fma_f32 v93, -v88, v92, 1.0
	v_fma_f32 v99, -v94, v98, 1.0
	v_fma_f32 v105, -v100, v104, 1.0
	v_fma_f32 v111, -v106, v110, 1.0
	v_fma_f32 v89, v93, v90, v92
	v_fma_f32 v95, v99, v96, v98
	v_fma_f32 v101, v105, v102, v104
	v_fma_f32 v107, v111, v108, v110
	v_div_fixup_f32 v89, v89, v88, 1.0
	v_div_fixup_f32 v95, v95, v94, 1.0
	v_div_fixup_f32 v101, v101, v100, 1.0
	v_div_fixup_f32 v107, v107, v106, 1.0
	v_mul_f32_e32 v89, v28, v89
	v_mul_f32_e32 v95, v29, v95
	v_mul_f32_e32 v101, v30, v101
	v_mul_f32_e32 v107, v31, v107
	v_mul_f32_e32 v89, v12, v89
	v_mul_f32_e32 v95, v13, v95
	v_mul_f32_e32 v101, v14, v101
	v_mul_f32_e32 v107, v15, v107
	v_cvt_pk_bf16_f32 v89, v89, v95
	v_cvt_pk_bf16_f32 v101, v101, v107
	s_nop 1
	v_mov_b32_dpp v95, v89 quad_perm:[1,0,3,2] row_mask:0xf bank_mask:0xf
	v_mov_b32_dpp v107, v101 quad_perm:[1,0,3,2] row_mask:0xf bank_mask:0xf
	v_perm_b32 v95, v95, v89, v118
	v_perm_b32 v107, v107, v101, v118
	ds_write_b32 v119, v95 offset:1536
	ds_write_b32 v119, v107 offset:1664
	ds_read_b128 v[120:123], v113
	ds_read_b128 v[124:127], v113 offset:1024
	s_waitcnt lgkmcnt(0)
	global_store_dwordx4 v114, v[120:123], s[98:99]
	s_add_u32 s98, s98, 0x16000
	s_addc_u32 s99, s99, 0
	global_store_dwordx4 v114, v[124:127], s[98:99]
	s_add_u32 s98, s98, 0x16000
	s_addc_u32 s99, s99, 0
	s_add_i32 s57, s57, s92
	s_cmpk_gt_i32 s57, 0x107f
	s_cbranch_scc1 .LBB0_1043

.Lodin4_nat:
	s_lshl_b32 s8, s7, 11
	s_add_u32 s8, s8, s9
	s_lshl_b32 s9, s6, 1
	s_add_u32 s8, s8, s9
	s_add_u32 s98, s90, s8
	s_addc_u32 s99, s91, 0
	v_and_b32_e32 v120, 1, v118
	v_lshlrev_b32_e32 v121, 6, v120
	v_sub_u32_e32 v121, v121, v120
	v_sub_u32_e32 v121, v121, v120
	v_add_u32_e32 v121, v121, v112
	v_cmp_eq_u32_e32 vcc, 1, v120
	v_mov_b32_e32 v120, 0x05040100
	v_mov_b32_e32 v122, 0x03020706
	s_nop 1
	v_cndmask_b32_e32 v120, v120, v122, vcc
	v_cvt_pk_bf16_f32 v64, v48, v49
	v_cvt_pk_bf16_f32 v65, v50, v51
	v_cvt_pk_bf16_f32 v66, v52, v53
	v_cvt_pk_bf16_f32 v67, v54, v55
	v_cvt_pk_bf16_f32 v68, v56, v57
	v_cvt_pk_bf16_f32 v69, v58, v59
	v_cvt_pk_bf16_f32 v70, v60, v61
	v_cvt_pk_bf16_f32 v71, v62, v63
	v_mov_b32_dpp v72, v64 quad_perm:[1,0,3,2] row_mask:0xf bank_mask:0xf
	v_mov_b32_dpp v73, v65 quad_perm:[1,0,3,2] row_mask:0xf bank_mask:0xf
	v_mov_b32_dpp v74, v66 quad_perm:[1,0,3,2] row_mask:0xf bank_mask:0xf
	v_mov_b32_dpp v75, v67 quad_perm:[1,0,3,2] row_mask:0xf bank_mask:0xf
	v_mov_b32_dpp v76, v68 quad_perm:[1,0,3,2] row_mask:0xf bank_mask:0xf
	v_mov_b32_dpp v77, v69 quad_perm:[1,0,3,2] row_mask:0xf bank_mask:0xf
	v_mov_b32_dpp v78, v70 quad_perm:[1,0,3,2] row_mask:0xf bank_mask:0xf
	v_mov_b32_dpp v79, v71 quad_perm:[1,0,3,2] row_mask:0xf bank_mask:0xf
	v_perm_b32 v72, v72, v64, v120
	v_perm_b32 v73, v73, v65, v120
	v_perm_b32 v74, v74, v66, v120
	v_perm_b32 v75, v75, v67, v120
	v_perm_b32 v76, v76, v68, v120
	v_perm_b32 v77, v77, v69, v120
	v_perm_b32 v78, v78, v70, v120
	v_perm_b32 v79, v79, v71, v120
	ds_write_b32 v121, v72
	ds_write_b32 v121, v73 offset:128
	ds_write_b32 v121, v74 offset:512
	ds_write_b32 v121, v75 offset:640
	ds_write_b32 v121, v76 offset:1024
	ds_write_b32 v121, v77 offset:1152
	ds_write_b32 v121, v78 offset:1536
	ds_write_b32 v121, v79 offset:1664
	ds_read_b128 v[80:83], v113
	ds_read_b128 v[84:87], v113 offset:1024
	v_cvt_pk_bf16_f32 v64, v16, v17
	v_cvt_pk_bf16_f32 v65, v18, v19
	v_cvt_pk_bf16_f32 v66, v20, v21
	v_cvt_pk_bf16_f32 v67, v22, v23
	v_cvt_pk_bf16_f32 v68, v24, v25
	v_cvt_pk_bf16_f32 v69, v26, v27
	v_cvt_pk_bf16_f32 v70, v28, v29
	v_cvt_pk_bf16_f32 v71, v30, v31
	v_mov_b32_dpp v72, v64 quad_perm:[1,0,3,2] row_mask:0xf bank_mask:0xf
	v_mov_b32_dpp v73, v65 quad_perm:[1,0,3,2] row_mask:0xf bank_mask:0xf
	v_mov_b32_dpp v74, v66 quad_perm:[1,0,3,2] row_mask:0xf bank_mask:0xf
	v_mov_b32_dpp v75, v67 quad_perm:[1,0,3,2] row_mask:0xf bank_mask:0xf
	v_mov_b32_dpp v76, v68 quad_perm:[1,0,3,2] row_mask:0xf bank_mask:0xf
	v_mov_b32_dpp v77, v69 quad_perm:[1,0,3,2] row_mask:0xf bank_mask:0xf
	v_mov_b32_dpp v78, v70 quad_perm:[1,0,3,2] row_mask:0xf bank_mask:0xf
	v_mov_b32_dpp v79, v71 quad_perm:[1,0,3,2] row_mask:0xf bank_mask:0xf
	v_perm_b32 v72, v72, v64, v120
	v_perm_b32 v73, v73, v65, v120
	v_perm_b32 v74, v74, v66, v120
	v_perm_b32 v75, v75, v67, v120
	v_perm_b32 v76, v76, v68, v120
	v_perm_b32 v77, v77, v69, v120
	v_perm_b32 v78, v78, v70, v120
	v_perm_b32 v79, v79, v71, v120
	ds_write_b32 v121, v72
	ds_write_b32 v121, v73 offset:128
	ds_write_b32 v121, v74 offset:512
	ds_write_b32 v121, v75 offset:640
	ds_write_b32 v121, v76 offset:1024
	ds_write_b32 v121, v77 offset:1152
	ds_write_b32 v121, v78 offset:1536
	ds_write_b32 v121, v79 offset:1664
	ds_read_b128 v[88:91], v113
	ds_read_b128 v[92:95], v113 offset:1024
	v_cvt_pk_bf16_f32 v64, v32, v33
	v_cvt_pk_bf16_f32 v65, v34, v35
	v_cvt_pk_bf16_f32 v66, v36, v37
	v_cvt_pk_bf16_f32 v67, v38, v39
	v_cvt_pk_bf16_f32 v68, v40, v41
	v_cvt_pk_bf16_f32 v69, v42, v43
	v_cvt_pk_bf16_f32 v70, v44, v45
	v_cvt_pk_bf16_f32 v71, v46, v47
	v_mov_b32_dpp v72, v64 quad_perm:[1,0,3,2] row_mask:0xf bank_mask:0xf
	v_mov_b32_dpp v73, v65 quad_perm:[1,0,3,2] row_mask:0xf bank_mask:0xf
	v_mov_b32_dpp v74, v66 quad_perm:[1,0,3,2] row_mask:0xf bank_mask:0xf
	v_mov_b32_dpp v75, v67 quad_perm:[1,0,3,2] row_mask:0xf bank_mask:0xf
	v_mov_b32_dpp v76, v68 quad_perm:[1,0,3,2] row_mask:0xf bank_mask:0xf
	v_mov_b32_dpp v77, v69 quad_perm:[1,0,3,2] row_mask:0xf bank_mask:0xf
	v_mov_b32_dpp v78, v70 quad_perm:[1,0,3,2] row_mask:0xf bank_mask:0xf
	v_mov_b32_dpp v79, v71 quad_perm:[1,0,3,2] row_mask:0xf bank_mask:0xf
	v_perm_b32 v72, v72, v64, v120
	v_perm_b32 v73, v73, v65, v120
	v_perm_b32 v74, v74, v66, v120
	v_perm_b32 v75, v75, v67, v120
	v_perm_b32 v76, v76, v68, v120
	v_perm_b32 v77, v77, v69, v120
	v_perm_b32 v78, v78, v70, v120
	v_perm_b32 v79, v79, v71, v120
	ds_write_b32 v121, v72
	ds_write_b32 v121, v73 offset:128
	ds_write_b32 v121, v74 offset:512
	ds_write_b32 v121, v75 offset:640
	ds_write_b32 v121, v76 offset:1024
	ds_write_b32 v121, v77 offset:1152
	ds_write_b32 v121, v78 offset:1536
	ds_write_b32 v121, v79 offset:1664
	ds_read_b128 v[96:99], v113
	ds_read_b128 v[100:103], v113 offset:1024
	v_cvt_pk_bf16_f32 v64, v0, v1
	v_cvt_pk_bf16_f32 v65, v2, v3
	v_cvt_pk_bf16_f32 v66, v4, v5
	v_cvt_pk_bf16_f32 v67, v6, v7
	v_cvt_pk_bf16_f32 v68, v8, v9
	v_cvt_pk_bf16_f32 v69, v10, v11
	v_cvt_pk_bf16_f32 v70, v12, v13
	v_cvt_pk_bf16_f32 v71, v14, v15
	v_mov_b32_dpp v72, v64 quad_perm:[1,0,3,2] row_mask:0xf bank_mask:0xf
	v_mov_b32_dpp v73, v65 quad_perm:[1,0,3,2] row_mask:0xf bank_mask:0xf
	v_mov_b32_dpp v74, v66 quad_perm:[1,0,3,2] row_mask:0xf bank_mask:0xf
	v_mov_b32_dpp v75, v67 quad_perm:[1,0,3,2] row_mask:0xf bank_mask:0xf
	v_mov_b32_dpp v76, v68 quad_perm:[1,0,3,2] row_mask:0xf bank_mask:0xf
	v_mov_b32_dpp v77, v69 quad_perm:[1,0,3,2] row_mask:0xf bank_mask:0xf
	v_mov_b32_dpp v78, v70 quad_perm:[1,0,3,2] row_mask:0xf bank_mask:0xf
	v_mov_b32_dpp v79, v71 quad_perm:[1,0,3,2] row_mask:0xf bank_mask:0xf
	v_perm_b32 v72, v72, v64, v120
	v_perm_b32 v73, v73, v65, v120
	v_perm_b32 v74, v74, v66, v120
	v_perm_b32 v75, v75, v67, v120
	v_perm_b32 v76, v76, v68, v120
	v_perm_b32 v77, v77, v69, v120
	v_perm_b32 v78, v78, v70, v120
	v_perm_b32 v79, v79, v71, v120
	ds_write_b32 v121, v72
	ds_write_b32 v121, v73 offset:128
	ds_write_b32 v121, v74 offset:512
	ds_write_b32 v121, v75 offset:640
	ds_write_b32 v121, v76 offset:1024
	ds_write_b32 v121, v77 offset:1152
	ds_write_b32 v121, v78 offset:1536
	ds_write_b32 v121, v79 offset:1664
	ds_read_b128 v[104:107], v113
	ds_read_b128 v[108:111], v113 offset:1024
	s_waitcnt lgkmcnt(15)
	global_store_dwordx4 v114, v[80:83], s[98:99]
	s_add_u32 s100, s98, 0x8000
	s_addc_u32 s101, s99, 0
	global_store_dwordx4 v114, v[84:87], s[100:101]
	global_store_dwordx4 v114, v[88:91], s[98:99] offset:64
	global_store_dwordx4 v114, v[92:95], s[100:101] offset:64
	s_add_u32 s98, s98, 0x10000
	s_addc_u32 s99, s99, 0
	s_waitcnt lgkmcnt(10)
	global_store_dwordx4 v114, v[96:99], s[98:99]
	s_add_u32 s100, s98, 0x8000
	s_addc_u32 s101, s99, 0
	global_store_dwordx4 v114, v[100:103], s[100:101]
	s_waitcnt lgkmcnt(0)
	global_store_dwordx4 v114, v[104:107], s[98:99] offset:64
	global_store_dwordx4 v114, v[108:111], s[100:101] offset:64
	s_branch .Lodin4_next

.LBB0_2283:
	v_lshl_or_b32 v115, v183, 3, v191
	v_lshrrev_b32_e32 v116, 6, v115
	v_and_b32_e32 v117, 63, v115
	v_lshlrev_b32_e32 v113, 11, v116
	v_add_u32_e32 v113, 0x10000, v113
	v_readfirstlane_b32 s100, v116
	v_and_b32_e32 v112, 31, v117
	v_lshl_add_u32 v112, v112, 1, v113
	v_lshrrev_b32_e32 v116, 5, v117
	v_lshl_add_u32 v112, v116, 8, v112
	v_lshl_add_u32 v113, v117, 4, v113
	v_lshrrev_b32_e32 v116, 2, v117
	v_mul_u32_u24_e32 v116, 0x1600, v116
	v_and_b32_e32 v114, 3, v117
	v_lshl_add_u32 v114, v114, 4, v116
	v_and_b32_e32 v118, 1, v117
	v_lshlrev_b32_e32 v119, 6, v118
	v_sub_u32_e32 v119, v119, v118
	v_sub_u32_e32 v119, v119, v118
	v_add_u32_e32 v119, v119, v112
	v_cmp_eq_u32_e32 vcc, 1, v118
	v_mov_b32_e32 v118, 0x05040100
	v_mov_b32_e32 v115, 0x03020706
	s_nop 1
	v_cndmask_b32_e32 v118, v118, v115, vcc
	s_lshr_b32 s101, s100, 1
	s_lshl_b32 s101, s101, 6
	s_add_u32 s101, s101, s48
	s_mul_i32 s101, s101, 0x1600
	s_and_b32 s100, s100, 1
	s_lshl_b32 s100, s100, 6
	s_add_u32 s100, s100, s49
	s_add_u32 s101, s101, s100
	s_add_u32 s98, s90, 0x3971900
	s_addc_u32 s99, s91, 0
	s_add_u32 s98, s98, s101
	s_addc_u32 s99, s99, 0
	v_mul_f32_e32 v64, 0xbfb8aa3b, v48
	v_mul_f32_e32 v70, 0xbfb8aa3b, v49
	v_mul_f32_e32 v76, 0xbfb8aa3b, v50
	v_mul_f32_e32 v82, 0xbfb8aa3b, v51
	v_exp_f32_e32 v64, v64
	v_exp_f32_e32 v70, v70
	v_exp_f32_e32 v76, v76
	v_exp_f32_e32 v82, v82
	v_add_f32_e32 v64, 1.0, v64
	v_add_f32_e32 v70, 1.0, v70
	v_add_f32_e32 v76, 1.0, v76
	v_add_f32_e32 v82, 1.0, v82
	v_rcp_f32_e32 v66, v64
	v_rcp_f32_e32 v72, v70
	v_rcp_f32_e32 v78, v76
	v_rcp_f32_e32 v84, v82
	v_fma_f32 v69, -v64, v66, 1.0
	v_fma_f32 v75, -v70, v72, 1.0
	v_fma_f32 v81, -v76, v78, 1.0
	v_fma_f32 v87, -v82, v84, 1.0
	v_fmac_f32_e32 v66, v69, v66
	v_fmac_f32_e32 v72, v75, v72
	v_fmac_f32_e32 v78, v81, v78
	v_fmac_f32_e32 v84, v87, v84
	v_fma_f32 v69, -v64, v66, 1.0
	v_mul_f32_e32 v88, 0xbfb8aa3b, v52
	v_fma_f32 v75, -v70, v72, 1.0
	v_mul_f32_e32 v94, 0xbfb8aa3b, v53
	v_fma_f32 v81, -v76, v78, 1.0
	v_mul_f32_e32 v100, 0xbfb8aa3b, v54
	v_fma_f32 v87, -v82, v84, 1.0
	v_mul_f32_e32 v106, 0xbfb8aa3b, v55
	v_fma_f32 v68, v69, v66, v66
	v_exp_f32_e32 v88, v88
	v_fma_f32 v74, v75, v72, v72
	v_exp_f32_e32 v94, v94
	v_fma_f32 v80, v81, v78, v78
	v_exp_f32_e32 v100, v100
	v_fma_f32 v86, v87, v84, v84
	v_exp_f32_e32 v106, v106
	v_fma_f32 v69, -v64, v68, 1.0
	v_add_f32_e32 v88, 1.0, v88
	v_fma_f32 v75, -v70, v74, 1.0
	v_add_f32_e32 v94, 1.0, v94
	v_fma_f32 v81, -v76, v80, 1.0
	v_add_f32_e32 v100, 1.0, v100
	v_fma_f32 v87, -v82, v86, 1.0
	v_add_f32_e32 v106, 1.0, v106
	v_fma_f32 v65, v69, v66, v68
	v_rcp_f32_e32 v90, v88
	v_fma_f32 v71, v75, v72, v74
	v_rcp_f32_e32 v96, v94
	v_fma_f32 v77, v81, v78, v80
	v_rcp_f32_e32 v102, v100
	v_fma_f32 v83, v87, v84, v86
	v_rcp_f32_e32 v108, v106
	v_fma_f32 v93, -v88, v90, 1.0
	v_fma_f32 v99, -v94, v96, 1.0
	v_fma_f32 v105, -v100, v102, 1.0
	v_fma_f32 v111, -v106, v108, 1.0
	v_fmac_f32_e32 v90, v93, v90
	v_fmac_f32_e32 v96, v99, v96
	v_fmac_f32_e32 v102, v105, v102
	v_fmac_f32_e32 v108, v111, v108
	v_div_fixup_f32 v65, v65, v64, 1.0
	v_div_fixup_f32 v71, v71, v70, 1.0
	v_div_fixup_f32 v77, v77, v76, 1.0
	v_div_fixup_f32 v83, v83, v82, 1.0
	v_mul_f32_e32 v65, v48, v65
	v_mul_f32_e32 v71, v49, v71
	v_mul_f32_e32 v77, v50, v77
	v_mul_f32_e32 v83, v51, v83
	v_mul_f32_e32 v65, v32, v65
	v_mul_f32_e32 v71, v33, v71
	v_mul_f32_e32 v77, v34, v77
	v_mul_f32_e32 v83, v35, v83
	v_cvt_pk_bf16_f32 v65, v65, v71
	v_cvt_pk_bf16_f32 v77, v77, v83
	s_nop 1
	v_mov_b32_dpp v71, v65 quad_perm:[1,0,3,2] row_mask:0xf bank_mask:0xf
	v_mov_b32_dpp v83, v77 quad_perm:[1,0,3,2] row_mask:0xf bank_mask:0xf
	v_perm_b32 v71, v71, v65, v118
	v_perm_b32 v83, v83, v77, v118
	ds_write_b32 v119, v71
	ds_write_b32 v119, v83 offset:128
	v_fma_f32 v93, -v88, v90, 1.0
	v_mul_f32_e32 v64, 0xbfb8aa3b, v56
	v_fma_f32 v99, -v94, v96, 1.0
	v_mul_f32_e32 v70, 0xbfb8aa3b, v57
	v_fma_f32 v105, -v100, v102, 1.0
	v_mul_f32_e32 v76, 0xbfb8aa3b, v58
	v_fma_f32 v111, -v106, v108, 1.0
	v_mul_f32_e32 v82, 0xbfb8aa3b, v59
	v_fma_f32 v92, v93, v90, v90
	v_exp_f32_e32 v64, v64
	v_fma_f32 v98, v99, v96, v96
	v_exp_f32_e32 v70, v70
	v_fma_f32 v104, v105, v102, v102
	v_exp_f32_e32 v76, v76
	v_fma_f32 v110, v111, v108, v108
	v_exp_f32_e32 v82, v82
	v_fma_f32 v93, -v88, v92, 1.0
	v_add_f32_e32 v64, 1.0, v64
	v_fma_f32 v99, -v94, v98, 1.0
	v_add_f32_e32 v70, 1.0, v70
	v_fma_f32 v105, -v100, v104, 1.0
	v_add_f32_e32 v76, 1.0, v76
	v_fma_f32 v111, -v106, v110, 1.0
	v_add_f32_e32 v82, 1.0, v82
	v_fma_f32 v89, v93, v90, v92
	v_rcp_f32_e32 v66, v64
	v_fma_f32 v95, v99, v96, v98
	v_rcp_f32_e32 v72, v70
	v_fma_f32 v101, v105, v102, v104
	v_rcp_f32_e32 v78, v76
	v_fma_f32 v107, v111, v108, v110
	v_rcp_f32_e32 v84, v82
	v_fma_f32 v69, -v64, v66, 1.0
	v_fma_f32 v75, -v70, v72, 1.0
	v_fma_f32 v81, -v76, v78, 1.0
	v_fma_f32 v87, -v82, v84, 1.0
	v_fmac_f32_e32 v66, v69, v66
	v_fmac_f32_e32 v72, v75, v72
	v_fmac_f32_e32 v78, v81, v78
	v_fmac_f32_e32 v84, v87, v84
	v_div_fixup_f32 v89, v89, v88, 1.0
	v_div_fixup_f32 v95, v95, v94, 1.0
	v_div_fixup_f32 v101, v101, v100, 1.0
	v_div_fixup_f32 v107, v107, v106, 1.0
	v_mul_f32_e32 v89, v52, v89
	v_mul_f32_e32 v95, v53, v95
	v_mul_f32_e32 v101, v54, v101
	v_mul_f32_e32 v107, v55, v107
	v_mul_f32_e32 v89, v36, v89
	v_mul_f32_e32 v95, v37, v95
	v_mul_f32_e32 v101, v38, v101
	v_mul_f32_e32 v107, v39, v107
	v_cvt_pk_bf16_f32 v89, v89, v95
	v_cvt_pk_bf16_f32 v101, v101, v107
	s_nop 1
	v_mov_b32_dpp v95, v89 quad_perm:[1,0,3,2] row_mask:0xf bank_mask:0xf
	v_mov_b32_dpp v107, v101 quad_perm:[1,0,3,2] row_mask:0xf bank_mask:0xf
	v_perm_b32 v95, v95, v89, v118
	v_perm_b32 v107, v107, v101, v118
	ds_write_b32 v119, v95 offset:512
	ds_write_b32 v119, v107 offset:640
	v_fma_f32 v69, -v64, v66, 1.0
	v_mul_f32_e32 v88, 0xbfb8aa3b, v60
	v_fma_f32 v75, -v70, v72, 1.0
	v_mul_f32_e32 v94, 0xbfb8aa3b, v61
	v_fma_f32 v81, -v76, v78, 1.0
	v_mul_f32_e32 v100, 0xbfb8aa3b, v62
	v_fma_f32 v87, -v82, v84, 1.0
	v_mul_f32_e32 v106, 0xbfb8aa3b, v63
	v_fma_f32 v68, v69, v66, v66
	v_exp_f32_e32 v88, v88
	v_fma_f32 v74, v75, v72, v72
	v_exp_f32_e32 v94, v94
	v_fma_f32 v80, v81, v78, v78
	v_exp_f32_e32 v100, v100
	v_fma_f32 v86, v87, v84, v84
	v_exp_f32_e32 v106, v106
	v_fma_f32 v69, -v64, v68, 1.0
	v_add_f32_e32 v88, 1.0, v88
	v_fma_f32 v75, -v70, v74, 1.0
	v_add_f32_e32 v94, 1.0, v94
	v_fma_f32 v81, -v76, v80, 1.0
	v_add_f32_e32 v100, 1.0, v100
	v_fma_f32 v87, -v82, v86, 1.0
	v_add_f32_e32 v106, 1.0, v106
	v_fma_f32 v65, v69, v66, v68
	v_rcp_f32_e32 v90, v88
	v_fma_f32 v71, v75, v72, v74
	v_rcp_f32_e32 v96, v94
	v_fma_f32 v77, v81, v78, v80
	v_rcp_f32_e32 v102, v100
	v_fma_f32 v83, v87, v84, v86
	v_rcp_f32_e32 v108, v106
	v_fma_f32 v93, -v88, v90, 1.0
	v_fma_f32 v99, -v94, v96, 1.0
	v_fma_f32 v105, -v100, v102, 1.0
	v_fma_f32 v111, -v106, v108, 1.0
	v_fmac_f32_e32 v90, v93, v90
	v_fmac_f32_e32 v96, v99, v96
	v_fmac_f32_e32 v102, v105, v102
	v_fmac_f32_e32 v108, v111, v108
	v_div_fixup_f32 v65, v65, v64, 1.0
	v_div_fixup_f32 v71, v71, v70, 1.0
	v_div_fixup_f32 v77, v77, v76, 1.0
	v_div_fixup_f32 v83, v83, v82, 1.0
	v_mul_f32_e32 v65, v56, v65
	v_mul_f32_e32 v71, v57, v71
	v_mul_f32_e32 v77, v58, v77
	v_mul_f32_e32 v83, v59, v83
	v_mul_f32_e32 v65, v40, v65
	v_mul_f32_e32 v71, v41, v71
	v_mul_f32_e32 v77, v42, v77
	v_mul_f32_e32 v83, v43, v83
	v_cvt_pk_bf16_f32 v65, v65, v71
	v_cvt_pk_bf16_f32 v77, v77, v83
	s_nop 1
	v_mov_b32_dpp v71, v65 quad_perm:[1,0,3,2] row_mask:0xf bank_mask:0xf
	v_mov_b32_dpp v83, v77 quad_perm:[1,0,3,2] row_mask:0xf bank_mask:0xf
	v_perm_b32 v71, v71, v65, v118
	v_perm_b32 v83, v83, v77, v118
	ds_write_b32 v119, v71 offset:1024
	ds_write_b32 v119, v83 offset:1152
	v_fma_f32 v93, -v88, v90, 1.0
	v_mul_f32_e32 v64, 0xbfb8aa3b, v16
	v_fma_f32 v99, -v94, v96, 1.0
	v_mul_f32_e32 v70, 0xbfb8aa3b, v17
	v_fma_f32 v105, -v100, v102, 1.0
	v_mul_f32_e32 v76, 0xbfb8aa3b, v18
	v_fma_f32 v111, -v106, v108, 1.0
	v_mul_f32_e32 v82, 0xbfb8aa3b, v19
	v_fma_f32 v92, v93, v90, v90
	v_exp_f32_e32 v64, v64
	v_fma_f32 v98, v99, v96, v96
	v_exp_f32_e32 v70, v70
	v_fma_f32 v104, v105, v102, v102
	v_exp_f32_e32 v76, v76
	v_fma_f32 v110, v111, v108, v108
	v_exp_f32_e32 v82, v82
	v_fma_f32 v93, -v88, v92, 1.0
	v_add_f32_e32 v64, 1.0, v64
	v_fma_f32 v99, -v94, v98, 1.0
	v_add_f32_e32 v70, 1.0, v70
	v_fma_f32 v105, -v100, v104, 1.0
	v_add_f32_e32 v76, 1.0, v76
	v_fma_f32 v111, -v106, v110, 1.0
	v_add_f32_e32 v82, 1.0, v82
	v_fma_f32 v89, v93, v90, v92
	v_rcp_f32_e32 v66, v64
	v_fma_f32 v95, v99, v96, v98
	v_rcp_f32_e32 v72, v70
	v_fma_f32 v101, v105, v102, v104
	v_rcp_f32_e32 v78, v76
	v_fma_f32 v107, v111, v108, v110
	v_rcp_f32_e32 v84, v82
	v_fma_f32 v69, -v64, v66, 1.0
	v_fma_f32 v75, -v70, v72, 1.0
	v_fma_f32 v81, -v76, v78, 1.0
	v_fma_f32 v87, -v82, v84, 1.0
	v_fmac_f32_e32 v66, v69, v66
	v_fmac_f32_e32 v72, v75, v72
	v_fmac_f32_e32 v78, v81, v78
	v_fmac_f32_e32 v84, v87, v84
	v_div_fixup_f32 v89, v89, v88, 1.0
	v_div_fixup_f32 v95, v95, v94, 1.0
	v_div_fixup_f32 v101, v101, v100, 1.0
	v_div_fixup_f32 v107, v107, v106, 1.0
	v_mul_f32_e32 v89, v60, v89
	v_mul_f32_e32 v95, v61, v95
	v_mul_f32_e32 v101, v62, v101
	v_mul_f32_e32 v107, v63, v107
	v_mul_f32_e32 v89, v44, v89
	v_mul_f32_e32 v95, v45, v95
	v_mul_f32_e32 v101, v46, v101
	v_mul_f32_e32 v107, v47, v107
	v_cvt_pk_bf16_f32 v89, v89, v95
	v_cvt_pk_bf16_f32 v101, v101, v107
	s_nop 1
	v_mov_b32_dpp v95, v89 quad_perm:[1,0,3,2] row_mask:0xf bank_mask:0xf
	v_mov_b32_dpp v107, v101 quad_perm:[1,0,3,2] row_mask:0xf bank_mask:0xf
	v_perm_b32 v95, v95, v89, v118
	v_perm_b32 v107, v107, v101, v118
	ds_write_b32 v119, v95 offset:1536
	ds_write_b32 v119, v107 offset:1664
	ds_read_b128 v[120:123], v113
	ds_read_b128 v[124:127], v113 offset:1024
	v_fma_f32 v69, -v64, v66, 1.0
	v_mul_f32_e32 v88, 0xbfb8aa3b, v20
	v_fma_f32 v75, -v70, v72, 1.0
	v_mul_f32_e32 v94, 0xbfb8aa3b, v21
	v_fma_f32 v81, -v76, v78, 1.0
	v_mul_f32_e32 v100, 0xbfb8aa3b, v22
	v_fma_f32 v87, -v82, v84, 1.0
	v_mul_f32_e32 v106, 0xbfb8aa3b, v23
	v_fma_f32 v68, v69, v66, v66
	v_exp_f32_e32 v88, v88
	v_fma_f32 v74, v75, v72, v72
	v_exp_f32_e32 v94, v94
	v_fma_f32 v80, v81, v78, v78
	v_exp_f32_e32 v100, v100
	v_fma_f32 v86, v87, v84, v84
	v_exp_f32_e32 v106, v106
	v_fma_f32 v69, -v64, v68, 1.0
	v_add_f32_e32 v88, 1.0, v88
	v_fma_f32 v75, -v70, v74, 1.0
	v_add_f32_e32 v94, 1.0, v94
	v_fma_f32 v81, -v76, v80, 1.0
	v_add_f32_e32 v100, 1.0, v100
	v_fma_f32 v87, -v82, v86, 1.0
	v_add_f32_e32 v106, 1.0, v106
	v_fma_f32 v65, v69, v66, v68
	v_rcp_f32_e32 v90, v88
	v_fma_f32 v71, v75, v72, v74
	v_rcp_f32_e32 v96, v94
	v_fma_f32 v77, v81, v78, v80
	v_rcp_f32_e32 v102, v100
	v_fma_f32 v83, v87, v84, v86
	v_rcp_f32_e32 v108, v106
	v_fma_f32 v93, -v88, v90, 1.0
	v_fma_f32 v99, -v94, v96, 1.0
	v_fma_f32 v105, -v100, v102, 1.0
	v_fma_f32 v111, -v106, v108, 1.0
	v_fmac_f32_e32 v90, v93, v90
	v_fmac_f32_e32 v96, v99, v96
	v_fmac_f32_e32 v102, v105, v102
	v_fmac_f32_e32 v108, v111, v108
	v_div_fixup_f32 v65, v65, v64, 1.0
	v_div_fixup_f32 v71, v71, v70, 1.0
	v_div_fixup_f32 v77, v77, v76, 1.0
	v_div_fixup_f32 v83, v83, v82, 1.0
	v_mul_f32_e32 v65, v16, v65
	v_mul_f32_e32 v71, v17, v71
	v_mul_f32_e32 v77, v18, v77
	v_mul_f32_e32 v83, v19, v83
	v_mul_f32_e32 v65, v0, v65
	v_mul_f32_e32 v71, v1, v71
	v_mul_f32_e32 v77, v2, v77
	v_mul_f32_e32 v83, v3, v83
	v_cvt_pk_bf16_f32 v65, v65, v71
	v_cvt_pk_bf16_f32 v77, v77, v83
	s_nop 1
	v_mov_b32_dpp v71, v65 quad_perm:[1,0,3,2] row_mask:0xf bank_mask:0xf
	v_mov_b32_dpp v83, v77 quad_perm:[1,0,3,2] row_mask:0xf bank_mask:0xf
	v_perm_b32 v71, v71, v65, v118
	v_perm_b32 v83, v83, v77, v118
	ds_write_b32 v119, v71
	ds_write_b32 v119, v83 offset:128
	v_fma_f32 v93, -v88, v90, 1.0
	v_mul_f32_e32 v64, 0xbfb8aa3b, v24
	v_fma_f32 v99, -v94, v96, 1.0
	v_mul_f32_e32 v70, 0xbfb8aa3b, v25
	v_fma_f32 v105, -v100, v102, 1.0
	v_mul_f32_e32 v76, 0xbfb8aa3b, v26
	v_fma_f32 v111, -v106, v108, 1.0
	v_mul_f32_e32 v82, 0xbfb8aa3b, v27
	v_fma_f32 v92, v93, v90, v90
	v_exp_f32_e32 v64, v64
	v_fma_f32 v98, v99, v96, v96
	v_exp_f32_e32 v70, v70
	v_fma_f32 v104, v105, v102, v102
	v_exp_f32_e32 v76, v76
	v_fma_f32 v110, v111, v108, v108
	v_exp_f32_e32 v82, v82
	v_fma_f32 v93, -v88, v92, 1.0
	v_add_f32_e32 v64, 1.0, v64
	v_fma_f32 v99, -v94, v98, 1.0
	v_add_f32_e32 v70, 1.0, v70
	v_fma_f32 v105, -v100, v104, 1.0
	v_add_f32_e32 v76, 1.0, v76
	v_fma_f32 v111, -v106, v110, 1.0
	v_add_f32_e32 v82, 1.0, v82
	v_fma_f32 v89, v93, v90, v92
	v_rcp_f32_e32 v66, v64
	v_fma_f32 v95, v99, v96, v98
	v_rcp_f32_e32 v72, v70
	v_fma_f32 v101, v105, v102, v104
	v_rcp_f32_e32 v78, v76
	v_fma_f32 v107, v111, v108, v110
	v_rcp_f32_e32 v84, v82
	v_fma_f32 v69, -v64, v66, 1.0
	v_fma_f32 v75, -v70, v72, 1.0
	v_fma_f32 v81, -v76, v78, 1.0
	v_fma_f32 v87, -v82, v84, 1.0
	v_fmac_f32_e32 v66, v69, v66
	v_fmac_f32_e32 v72, v75, v72
	v_fmac_f32_e32 v78, v81, v78
	v_fmac_f32_e32 v84, v87, v84
	s_waitcnt lgkmcnt(0)
	global_store_dwordx4 v114, v[120:123], s[98:99]
	s_add_u32 s98, s98, 0x16000
	s_addc_u32 s99, s99, 0
	global_store_dwordx4 v114, v[124:127], s[98:99]
	s_add_u32 s98, s98, 0x16000
	s_addc_u32 s99, s99, 0
	v_div_fixup_f32 v89, v89, v88, 1.0
	v_div_fixup_f32 v95, v95, v94, 1.0
	v_div_fixup_f32 v101, v101, v100, 1.0
	v_div_fixup_f32 v107, v107, v106, 1.0
	v_mul_f32_e32 v89, v20, v89
	v_mul_f32_e32 v95, v21, v95
	v_mul_f32_e32 v101, v22, v101
	v_mul_f32_e32 v107, v23, v107
	v_mul_f32_e32 v89, v4, v89
	v_mul_f32_e32 v95, v5, v95
	v_mul_f32_e32 v101, v6, v101
	v_mul_f32_e32 v107, v7, v107
	v_cvt_pk_bf16_f32 v89, v89, v95
	v_cvt_pk_bf16_f32 v101, v101, v107
	s_nop 1
	v_mov_b32_dpp v95, v89 quad_perm:[1,0,3,2] row_mask:0xf bank_mask:0xf
	v_mov_b32_dpp v107, v101 quad_perm:[1,0,3,2] row_mask:0xf bank_mask:0xf
	v_perm_b32 v95, v95, v89, v118
	v_perm_b32 v107, v107, v101, v118
	ds_write_b32 v119, v95 offset:512
	ds_write_b32 v119, v107 offset:640
	v_fma_f32 v69, -v64, v66, 1.0
	v_mul_f32_e32 v88, 0xbfb8aa3b, v28
	v_fma_f32 v75, -v70, v72, 1.0
	v_mul_f32_e32 v94, 0xbfb8aa3b, v29
	v_fma_f32 v81, -v76, v78, 1.0
	v_mul_f32_e32 v100, 0xbfb8aa3b, v30
	v_fma_f32 v87, -v82, v84, 1.0
	v_mul_f32_e32 v106, 0xbfb8aa3b, v31
	v_fma_f32 v68, v69, v66, v66
	v_exp_f32_e32 v88, v88
	v_fma_f32 v74, v75, v72, v72
	v_exp_f32_e32 v94, v94
	v_fma_f32 v80, v81, v78, v78
	v_exp_f32_e32 v100, v100
	v_fma_f32 v86, v87, v84, v84
	v_exp_f32_e32 v106, v106
	v_fma_f32 v69, -v64, v68, 1.0
	v_add_f32_e32 v88, 1.0, v88
	v_fma_f32 v75, -v70, v74, 1.0
	v_add_f32_e32 v94, 1.0, v94
	v_fma_f32 v81, -v76, v80, 1.0
	v_add_f32_e32 v100, 1.0, v100
	v_fma_f32 v87, -v82, v86, 1.0
	v_add_f32_e32 v106, 1.0, v106
	v_fma_f32 v65, v69, v66, v68
	v_rcp_f32_e32 v90, v88
	v_fma_f32 v71, v75, v72, v74
	v_rcp_f32_e32 v96, v94
	v_fma_f32 v77, v81, v78, v80
	v_rcp_f32_e32 v102, v100
	v_fma_f32 v83, v87, v84, v86
	v_rcp_f32_e32 v108, v106
	v_fma_f32 v93, -v88, v90, 1.0
	v_fma_f32 v99, -v94, v96, 1.0
	v_fma_f32 v105, -v100, v102, 1.0
	v_fma_f32 v111, -v106, v108, 1.0
	v_fmac_f32_e32 v90, v93, v90
	v_fmac_f32_e32 v96, v99, v96
	v_fmac_f32_e32 v102, v105, v102
	v_fmac_f32_e32 v108, v111, v108
	v_div_fixup_f32 v65, v65, v64, 1.0
	v_div_fixup_f32 v71, v71, v70, 1.0
	v_div_fixup_f32 v77, v77, v76, 1.0
	v_div_fixup_f32 v83, v83, v82, 1.0
	v_mul_f32_e32 v65, v24, v65
	v_mul_f32_e32 v71, v25, v71
	v_mul_f32_e32 v77, v26, v77
	v_mul_f32_e32 v83, v27, v83
	v_mul_f32_e32 v65, v8, v65
	v_mul_f32_e32 v71, v9, v71
	v_mul_f32_e32 v77, v10, v77
	v_mul_f32_e32 v83, v11, v83
	v_cvt_pk_bf16_f32 v65, v65, v71
	v_cvt_pk_bf16_f32 v77, v77, v83
	s_nop 1
	v_mov_b32_dpp v71, v65 quad_perm:[1,0,3,2] row_mask:0xf bank_mask:0xf
	v_mov_b32_dpp v83, v77 quad_perm:[1,0,3,2] row_mask:0xf bank_mask:0xf
	v_perm_b32 v71, v71, v65, v118
	v_perm_b32 v83, v83, v77, v118
	ds_write_b32 v119, v71 offset:1024
	ds_write_b32 v119, v83 offset:1152
	v_fma_f32 v93, -v88, v90, 1.0
	v_fma_f32 v99, -v94, v96, 1.0
	v_fma_f32 v105, -v100, v102, 1.0
	v_fma_f32 v111, -v106, v108, 1.0
	v_fma_f32 v92, v93, v90, v90
	v_fma_f32 v98, v99, v96, v96
	v_fma_f32 v104, v105, v102, v102
	v_fma_f32 v110, v111, v108, v108
	v_fma_f32 v93, -v88, v92, 1.0
	v_fma_f32 v99, -v94, v98, 1.0
	v_fma_f32 v105, -v100, v104, 1.0
	v_fma_f32 v111, -v106, v110, 1.0
	v_fma_f32 v89, v93, v90, v92
	v_fma_f32 v95, v99, v96, v98
	v_fma_f32 v101, v105, v102, v104
	v_fma_f32 v107, v111, v108, v110
	v_div_fixup_f32 v89, v89, v88, 1.0
	v_div_fixup_f32 v95, v95, v94, 1.0
	v_div_fixup_f32 v101, v101, v100, 1.0
	v_div_fixup_f32 v107, v107, v106, 1.0
	v_mul_f32_e32 v89, v28, v89
	v_mul_f32_e32 v95, v29, v95
	v_mul_f32_e32 v101, v30, v101
	v_mul_f32_e32 v107, v31, v107
	v_mul_f32_e32 v89, v12, v89
	v_mul_f32_e32 v95, v13, v95
	v_mul_f32_e32 v101, v14, v101
	v_mul_f32_e32 v107, v15, v107
	v_cvt_pk_bf16_f32 v89, v89, v95
	v_cvt_pk_bf16_f32 v101, v101, v107
	s_nop 1
	v_mov_b32_dpp v95, v89 quad_perm:[1,0,3,2] row_mask:0xf bank_mask:0xf
	v_mov_b32_dpp v107, v101 quad_perm:[1,0,3,2] row_mask:0xf bank_mask:0xf
	v_perm_b32 v95, v95, v89, v118
	v_perm_b32 v107, v107, v101, v118
	ds_write_b32 v119, v95 offset:1536
	ds_write_b32 v119, v107 offset:1664
	ds_read_b128 v[120:123], v113
	ds_read_b128 v[124:127], v113 offset:1024
	s_waitcnt lgkmcnt(0)
	global_store_dwordx4 v114, v[120:123], s[98:99]
	s_add_u32 s98, s98, 0x16000
	s_addc_u32 s99, s99, 0
	global_store_dwordx4 v114, v[124:127], s[98:99]
	s_add_u32 s98, s98, 0x16000
	s_addc_u32 s99, s99, 0
	s_add_i32 s47, s47, s92
	s_cmpk_gt_i32 s47, 0x107f
	s_cbranch_scc1 .LBB0_2292
